# P4: split-phase wave-pair rendezvous (arrive after staging writes, second arrive after PV reads; waits deferred to the next chunk's reads / first staging write, counter reads issued early)
# baseline (speedup 1.0000x reference)
; #define LAS __attribute__((address_space(3)))
; #define P4_LOAD(ch) do { const u32x4 kk_ = *(const LAS u32x4*)(idxs + tok * 256 + (ch) * 32 + wrow); \
;       _Pragma("unroll") for (int i = 0; i < 8; ++i) { \
;       const int key = (int)((kk_[i >> 1] >> (16 * (i & 1))) & 0xffffu); stg[i] = *(const u32x4*)(cbase + (size_t)key * 256); } } while (0)
; #define P4_WRITE(bufp) do { _Pragma("unroll") for (int i = 0; i < 8; ++i) \
;       *(LAS u32x4*)((bufp) + (wrow + i) * CROW + 16 * (wch ^ (lane >> 5))) = stg[i]; } while (0)
; __device__ __forceinline__ void pair_sync(LAS unsigned* cnt, unsigned target, int lane) {
;   asm volatile("" ::: "memory");
;   if (lane == 0) __hip_atomic_fetch_add(cnt, 1u, __ATOMIC_RELAXED, __HIP_MEMORY_SCOPE_WORKGROUP);
;   while (__hip_atomic_load(cnt, __ATOMIC_RELAXED, __HIP_MEMORY_SCOPE_WORKGROUP) < target) __builtin_amdgcn_s_sleep(1);
;   asm volatile("" ::: "memory");
; }
; __device__ __forceinline__ void p4_attn(const Params& p, unsigned char* lds, int bid, int nb, bool dry) {
;     ...
;     for (int ch = 0; ch < nch; ++ch) {
;       LAS unsigned char* cb = cbuf + (ch & 1) * CBUF + tok * CTOK;
;       if (ch + 1 < nch) { P4_WRITE(cbuf + ((ch + 1) & 1) * CBUF + tok * CTOK); if (ch + 2 < nch) P4_LOAD(ch + 2); }
;       f32x4 s0 = (f32x4){0.f, 0.f, 0.f, 0.f}, s1 = (f32x4){0.f, 0.f, 0.f, 0.f};
; #pragma unroll
;       for (int s = 0; s < 8; ++s) {
;         const bf16x8 a0 = *(const LAS bf16x8*)(cb + r16 * CROW + s * 64 + qoff);
;         const bf16x8 a1 = *(const LAS bf16x8*)(cb + (16 + r16) * CROW + s * 64 + qoff);
;         s0 = __builtin_amdgcn_mfma_f32_16x16x32_bf16(a0, qB[s], s0, 0, 0, 0);
;         s1 = __builtin_amdgcn_mfma_f32_16x16x32_bf16(a1, qB[s], s1, 0, 0, 0);
;       }
.LBB0_1005:
	s_add_i32 s27, s10, 2
	s_cmp_ge_u32 s27, s21
	s_cbranch_scc1 .Lp4_w1
	s_bitcmp1_b32 s10, 0
	s_cbranch_scc1 .Lp4_w2_odd
	s_bitcmp1_b32 s10, 0
	s_cselect_b32 s11, 0x11000, 0
	s_add_i32 s12, s5, s11
	s_lshl_b32 s13, s10, 5
	v_add3_u32 v2, s12, v168, v162
	v_mov_b32_e32 v139, s2
	ds_read_b32 v138, v139
	s_add_i32 s27, s10, 3
	v_lshl_add_u32 v3, s27, 6, v167
	ds_read_b128 v[196:199], v3
	ds_read_b128 v[234:237], v2
	ds_read_b128 v[238:241], v2 offset:8704
	ds_read_b128 v[242:245], v2 offset:64
	ds_read_b128 v[246:249], v2 offset:8768
	ds_read_b128 v[250:253], v2 offset:128
	ds_read_b128 v[188:191], v2 offset:8832
	v_or_b32_e32 v0, s13, v148
	v_lshl_add_u32 v3, v0, 1, s3
	s_bitcmp1_b32 s23, 0
	s_cselect_b32 s11, 0x11000, 0
	v_add_u32_e32 v201, s11, v170
	s_waitcnt lgkmcnt(5)
	v_mfma_f32_16x16x32_bf16 v[140:143], v[234:237], v[4:7], 0
	ds_read_b128 v[234:237], v2 offset:192
	s_waitcnt lgkmcnt(5)
	v_mfma_f32_16x16x32_bf16 v[144:147], v[238:241], v[4:7], 0
	ds_read_b128 v[238:241], v2 offset:8896
	ds_read2_b64 v[184:187], v3 offset1:4
	s_waitcnt lgkmcnt(6)
	v_mfma_f32_16x16x32_bf16 v[140:143], v[242:245], v[8:11], v[140:143]
	ds_read_b128 v[242:245], v2 offset:256
	v_cmp_le_u32_e32 vcc, s19, v138
	s_cbranch_vccz .Lp4_wbs_W20
.Lp4_wbk_W20:
	s_waitcnt vmcnt(15)
	ds_write_b128 v201, v[202:205]
	s_waitcnt lgkmcnt(7)
	v_mfma_f32_16x16x32_bf16 v[144:147], v[246:249], v[8:11], v[144:147]
	ds_read_b128 v[246:249], v2 offset:8960
	s_waitcnt vmcnt(14)
	ds_write_b128 v201, v[206:209] offset:544
	s_waitcnt lgkmcnt(8)
	v_mfma_f32_16x16x32_bf16 v[140:143], v[250:253], v[12:15], v[140:143]
	ds_read_b128 v[250:253], v2 offset:320
	s_waitcnt vmcnt(13)
	ds_write_b128 v201, v[210:213] offset:1088
	s_waitcnt lgkmcnt(9)
	v_mfma_f32_16x16x32_bf16 v[144:147], v[188:191], v[12:15], v[144:147]
	ds_read_b128 v[188:191], v2 offset:9024
	s_waitcnt vmcnt(12)
	ds_write_b128 v201, v[214:217] offset:1632
	s_waitcnt lgkmcnt(10)
	v_mfma_f32_16x16x32_bf16 v[140:143], v[234:237], v[16:19], v[140:143]
	ds_read_b128 v[234:237], v2 offset:384
	s_waitcnt vmcnt(11)
	ds_write_b128 v201, v[218:221] offset:2176
	s_waitcnt lgkmcnt(11)
	v_mfma_f32_16x16x32_bf16 v[144:147], v[238:241], v[16:19], v[144:147]
	ds_read_b128 v[238:241], v2 offset:9088
	s_waitcnt vmcnt(10)
	ds_write_b128 v201, v[222:225] offset:2720
	s_waitcnt lgkmcnt(11)
	v_mfma_f32_16x16x32_bf16 v[140:143], v[242:245], v[20:23], v[140:143]
	ds_read_b128 v[242:245], v2 offset:448
	s_waitcnt vmcnt(9)
	ds_write_b128 v201, v[226:229] offset:3264
	s_waitcnt lgkmcnt(11)
	v_mfma_f32_16x16x32_bf16 v[144:147], v[246:249], v[20:23], v[144:147]
	ds_read_b128 v[246:249], v2 offset:9152
	s_waitcnt vmcnt(8)
	ds_write_b128 v201, v[230:233] offset:3808
	s_waitcnt lgkmcnt(11)
	v_mfma_f32_16x16x32_bf16 v[140:143], v[250:253], v[24:27], v[140:143]
	s_waitcnt lgkmcnt(9)
	v_mfma_f32_16x16x32_bf16 v[144:147], v[188:191], v[24:27], v[144:147]
	s_waitcnt lgkmcnt(7)
	v_mfma_f32_16x16x32_bf16 v[140:143], v[234:237], v[28:31], v[140:143]
	s_waitcnt lgkmcnt(5)
	v_mfma_f32_16x16x32_bf16 v[144:147], v[238:241], v[28:31], v[144:147]
	s_waitcnt lgkmcnt(3)
	v_mfma_f32_16x16x32_bf16 v[140:143], v[242:245], v[32:35], v[140:143]
	s_waitcnt lgkmcnt(1)
	v_mfma_f32_16x16x32_bf16 v[144:147], v[246:249], v[32:35], v[144:147]
	s_add_i32 s27, s10, 3
	s_cmp_ge_u32 s27, s21
	s_cbranch_scc1 .Lp4_softmax
	s_waitcnt lgkmcnt(0)
	v_lshlrev_b32_e32 v0, 9, v196
	v_and_b32_e32 v0, 0x1fffe00, v0
	v_lshl_add_u64 v[2:3], v[160:161], 0, v[0:1]
	v_lshlrev_b32_sdwa v0, v171, v196 dst_sel:DWORD dst_unused:UNUSED_PAD src0_sel:DWORD src1_sel:WORD_1
	v_lshl_add_u64 v[206:207], v[160:161], 0, v[0:1]
	global_load_dwordx4 v[202:205], v[2:3], off
	global_load_dwordx4 v[206:209], v[206:207], off
	v_lshlrev_b32_e32 v0, 9, v197
	v_and_b32_e32 v0, 0x1fffe00, v0
	v_lshl_add_u64 v[2:3], v[160:161], 0, v[0:1]
	v_lshlrev_b32_sdwa v0, v171, v197 dst_sel:DWORD dst_unused:UNUSED_PAD src0_sel:DWORD src1_sel:WORD_1
	v_lshl_add_u64 v[214:215], v[160:161], 0, v[0:1]
	global_load_dwordx4 v[210:213], v[2:3], off
	global_load_dwordx4 v[214:217], v[214:215], off
	v_lshlrev_b32_e32 v0, 9, v198
	v_and_b32_e32 v0, 0x1fffe00, v0
	v_lshl_add_u64 v[2:3], v[160:161], 0, v[0:1]
	v_lshlrev_b32_sdwa v0, v171, v198 dst_sel:DWORD dst_unused:UNUSED_PAD src0_sel:DWORD src1_sel:WORD_1
	v_lshl_add_u64 v[222:223], v[160:161], 0, v[0:1]
	global_load_dwordx4 v[218:221], v[2:3], off
	global_load_dwordx4 v[222:225], v[222:223], off
	v_lshlrev_b32_e32 v0, 9, v199
	v_and_b32_e32 v0, 0x1fffe00, v0
	v_lshl_add_u64 v[2:3], v[160:161], 0, v[0:1]
	v_lshlrev_b32_sdwa v0, v171, v199 dst_sel:DWORD dst_unused:UNUSED_PAD src0_sel:DWORD src1_sel:WORD_1
	v_lshl_add_u64 v[230:231], v[160:161], 0, v[0:1]
	global_load_dwordx4 v[226:229], v[2:3], off
	global_load_dwordx4 v[230:233], v[230:231], off
	s_branch .Lp4_softmax
; #define LAS __attribute__((address_space(3)))
; #define P4_LOAD(ch) do { const u32x4 kk_ = *(const LAS u32x4*)(idxs + tok * 256 + (ch) * 32 + wrow); \
;       _Pragma("unroll") for (int i = 0; i < 8; ++i) { \
;       const int key = (int)((kk_[i >> 1] >> (16 * (i & 1))) & 0xffffu); stg[i] = *(const u32x4*)(cbase + (size_t)key * 256); } } while (0)
; #define P4_WRITE(bufp) do { _Pragma("unroll") for (int i = 0; i < 8; ++i) \
;       *(LAS u32x4*)((bufp) + (wrow + i) * CROW + 16 * (wch ^ (lane >> 5))) = stg[i]; } while (0)
; __device__ __forceinline__ void pair_sync(LAS unsigned* cnt, unsigned target, int lane) {
;   asm volatile("" ::: "memory");
;   if (lane == 0) __hip_atomic_fetch_add(cnt, 1u, __ATOMIC_RELAXED, __HIP_MEMORY_SCOPE_WORKGROUP);
;   while (__hip_atomic_load(cnt, __ATOMIC_RELAXED, __HIP_MEMORY_SCOPE_WORKGROUP) < target) __builtin_amdgcn_s_sleep(1);
;   asm volatile("" ::: "memory");
; }
; __device__ __forceinline__ void p4_attn(const Params& p, unsigned char* lds, int bid, int nb, bool dry) {
;     ...
;     for (int ch = 0; ch < nch; ++ch) {
;       LAS unsigned char* cb = cbuf + (ch & 1) * CBUF + tok * CTOK;
;       if (ch + 1 < nch) { P4_WRITE(cbuf + ((ch + 1) & 1) * CBUF + tok * CTOK); if (ch + 2 < nch) P4_LOAD(ch + 2); }
;       f32x4 s0 = (f32x4){0.f, 0.f, 0.f, 0.f}, s1 = (f32x4){0.f, 0.f, 0.f, 0.f};
; #pragma unroll
;       for (int s = 0; s < 8; ++s) {
;         const bf16x8 a0 = *(const LAS bf16x8*)(cb + r16 * CROW + s * 64 + qoff);
;         const bf16x8 a1 = *(const LAS bf16x8*)(cb + (16 + r16) * CROW + s * 64 + qoff);
;         s0 = __builtin_amdgcn_mfma_f32_16x16x32_bf16(a0, qB[s], s0, 0, 0, 0);
;         s1 = __builtin_amdgcn_mfma_f32_16x16x32_bf16(a1, qB[s], s1, 0, 0, 0);
;       }
.Lp4_wbs_W20:
	s_sleep 1
	ds_read_b32 v138, v139
	s_waitcnt lgkmcnt(0)
	v_cmp_gt_u32_e32 vcc, s19, v138
	s_cbranch_vccnz .Lp4_wbs_W20
	s_branch .Lp4_wbk_W20
.Lp4_w2_odd:
	s_bitcmp1_b32 s10, 0
	s_cselect_b32 s11, 0x11000, 0
	s_add_i32 s12, s5, s11
	s_lshl_b32 s13, s10, 5
	v_add3_u32 v2, s12, v168, v162
	v_mov_b32_e32 v139, s2
	ds_read_b32 v138, v139
	s_add_i32 s27, s10, 3
	v_lshl_add_u32 v3, s27, 6, v167
	ds_read_b128 v[196:199], v3
	ds_read_b128 v[234:237], v2
	ds_read_b128 v[238:241], v2 offset:8704
	ds_read_b128 v[242:245], v2 offset:64
	ds_read_b128 v[246:249], v2 offset:8768
	ds_read_b128 v[250:253], v2 offset:128
	ds_read_b128 v[188:191], v2 offset:8832
	v_or_b32_e32 v0, s13, v148
	v_lshl_add_u32 v3, v0, 1, s3
	s_bitcmp1_b32 s23, 0
	s_cselect_b32 s11, 0x11000, 0
	v_add_u32_e32 v201, s11, v170
	s_waitcnt lgkmcnt(5)
	v_mfma_f32_16x16x32_bf16 v[140:143], v[234:237], v[4:7], 0
	ds_read_b128 v[234:237], v2 offset:192
	s_waitcnt lgkmcnt(5)
	v_mfma_f32_16x16x32_bf16 v[144:147], v[238:241], v[4:7], 0
	ds_read_b128 v[238:241], v2 offset:8896
	ds_read2_b64 v[184:187], v3 offset1:4
	s_waitcnt lgkmcnt(6)
	v_mfma_f32_16x16x32_bf16 v[140:143], v[242:245], v[8:11], v[140:143]
	ds_read_b128 v[242:245], v2 offset:256
	v_cmp_le_u32_e32 vcc, s19, v138
	s_cbranch_vccz .Lp4_wbs_W21
.Lp4_wbk_W21:
	s_waitcnt vmcnt(15)
	ds_write_b128 v201, v[44:47]
	s_waitcnt lgkmcnt(7)
	v_mfma_f32_16x16x32_bf16 v[144:147], v[246:249], v[8:11], v[144:147]
	ds_read_b128 v[246:249], v2 offset:8960
	s_waitcnt vmcnt(14)
	ds_write_b128 v201, v[48:51] offset:544
	s_waitcnt lgkmcnt(8)
	v_mfma_f32_16x16x32_bf16 v[140:143], v[250:253], v[12:15], v[140:143]
	ds_read_b128 v[250:253], v2 offset:320
	s_waitcnt vmcnt(13)
	ds_write_b128 v201, v[60:63] offset:1088
	s_waitcnt lgkmcnt(9)
	v_mfma_f32_16x16x32_bf16 v[144:147], v[188:191], v[12:15], v[144:147]
	ds_read_b128 v[188:191], v2 offset:9024
	s_waitcnt vmcnt(12)
	ds_write_b128 v201, v[68:71] offset:1632
	s_waitcnt lgkmcnt(10)
	v_mfma_f32_16x16x32_bf16 v[140:143], v[234:237], v[16:19], v[140:143]
	ds_read_b128 v[234:237], v2 offset:384
	s_waitcnt vmcnt(11)
	ds_write_b128 v201, v[84:87] offset:2176
	s_waitcnt lgkmcnt(11)
	v_mfma_f32_16x16x32_bf16 v[144:147], v[238:241], v[16:19], v[144:147]
	ds_read_b128 v[238:241], v2 offset:9088
	s_waitcnt vmcnt(10)
	ds_write_b128 v201, v[88:91] offset:2720
	s_waitcnt lgkmcnt(11)
	v_mfma_f32_16x16x32_bf16 v[140:143], v[242:245], v[20:23], v[140:143]
	ds_read_b128 v[242:245], v2 offset:448
	s_waitcnt vmcnt(9)
	ds_write_b128 v201, v[100:103] offset:3264
	s_waitcnt lgkmcnt(11)
	v_mfma_f32_16x16x32_bf16 v[144:147], v[246:249], v[20:23], v[144:147]
	ds_read_b128 v[246:249], v2 offset:9152
	s_waitcnt vmcnt(8)
	ds_write_b128 v201, v[108:111] offset:3808
	s_waitcnt lgkmcnt(11)
	v_mfma_f32_16x16x32_bf16 v[140:143], v[250:253], v[24:27], v[140:143]
	s_waitcnt lgkmcnt(9)
	v_mfma_f32_16x16x32_bf16 v[144:147], v[188:191], v[24:27], v[144:147]
	s_waitcnt lgkmcnt(7)
	v_mfma_f32_16x16x32_bf16 v[140:143], v[234:237], v[28:31], v[140:143]
	s_waitcnt lgkmcnt(5)
	v_mfma_f32_16x16x32_bf16 v[144:147], v[238:241], v[28:31], v[144:147]
	s_waitcnt lgkmcnt(3)
	v_mfma_f32_16x16x32_bf16 v[140:143], v[242:245], v[32:35], v[140:143]
	s_waitcnt lgkmcnt(1)
	v_mfma_f32_16x16x32_bf16 v[144:147], v[246:249], v[32:35], v[144:147]
	s_add_i32 s27, s10, 3
	s_cmp_ge_u32 s27, s21
	s_cbranch_scc1 .Lp4_softmax
	s_waitcnt lgkmcnt(0)
	v_lshlrev_b32_e32 v0, 9, v196
	v_and_b32_e32 v0, 0x1fffe00, v0
	v_lshl_add_u64 v[2:3], v[160:161], 0, v[0:1]
	v_lshlrev_b32_sdwa v0, v171, v196 dst_sel:DWORD dst_unused:UNUSED_PAD src0_sel:DWORD src1_sel:WORD_1
	v_lshl_add_u64 v[48:49], v[160:161], 0, v[0:1]
	global_load_dwordx4 v[44:47], v[2:3], off
	global_load_dwordx4 v[48:51], v[48:49], off
	v_lshlrev_b32_e32 v0, 9, v197
	v_and_b32_e32 v0, 0x1fffe00, v0
	v_lshl_add_u64 v[2:3], v[160:161], 0, v[0:1]
	v_lshlrev_b32_sdwa v0, v171, v197 dst_sel:DWORD dst_unused:UNUSED_PAD src0_sel:DWORD src1_sel:WORD_1
	v_lshl_add_u64 v[68:69], v[160:161], 0, v[0:1]
	global_load_dwordx4 v[60:63], v[2:3], off
	global_load_dwordx4 v[68:71], v[68:69], off
	v_lshlrev_b32_e32 v0, 9, v198
	v_and_b32_e32 v0, 0x1fffe00, v0
	v_lshl_add_u64 v[2:3], v[160:161], 0, v[0:1]
	v_lshlrev_b32_sdwa v0, v171, v198 dst_sel:DWORD dst_unused:UNUSED_PAD src0_sel:DWORD src1_sel:WORD_1
	v_lshl_add_u64 v[88:89], v[160:161], 0, v[0:1]
	global_load_dwordx4 v[84:87], v[2:3], off
	global_load_dwordx4 v[88:91], v[88:89], off
	v_lshlrev_b32_e32 v0, 9, v199
	v_and_b32_e32 v0, 0x1fffe00, v0
	v_lshl_add_u64 v[2:3], v[160:161], 0, v[0:1]
	v_lshlrev_b32_sdwa v0, v171, v199 dst_sel:DWORD dst_unused:UNUSED_PAD src0_sel:DWORD src1_sel:WORD_1
	v_lshl_add_u64 v[108:109], v[160:161], 0, v[0:1]
	global_load_dwordx4 v[100:103], v[2:3], off
	global_load_dwordx4 v[108:111], v[108:109], off
	s_branch .Lp4_softmax

; #define LAS __attribute__((address_space(3)))
; #define P4_LOAD(ch) do { const u32x4 kk_ = *(const LAS u32x4*)(idxs + tok * 256 + (ch) * 32 + wrow); \
;       _Pragma("unroll") for (int i = 0; i < 8; ++i) { \
;       const int key = (int)((kk_[i >> 1] >> (16 * (i & 1))) & 0xffffu); stg[i] = *(const u32x4*)(cbase + (size_t)key * 256); } } while (0)
; #define P4_WRITE(bufp) do { _Pragma("unroll") for (int i = 0; i < 8; ++i) \
;       *(LAS u32x4*)((bufp) + (wrow + i) * CROW + 16 * (wch ^ (lane >> 5))) = stg[i]; } while (0)
; __device__ __forceinline__ void pair_sync(LAS unsigned* cnt, unsigned target, int lane) {
;   asm volatile("" ::: "memory");
;   if (lane == 0) __hip_atomic_fetch_add(cnt, 1u, __ATOMIC_RELAXED, __HIP_MEMORY_SCOPE_WORKGROUP);
;   while (__hip_atomic_load(cnt, __ATOMIC_RELAXED, __HIP_MEMORY_SCOPE_WORKGROUP) < target) __builtin_amdgcn_s_sleep(1);
;   asm volatile("" ::: "memory");
; }
; __device__ __forceinline__ void p4_attn(const Params& p, unsigned char* lds, int bid, int nb, bool dry) {
;     ...
;     for (int ch = 0; ch < nch; ++ch) {
;       LAS unsigned char* cb = cbuf + (ch & 1) * CBUF + tok * CTOK;
;       if (ch + 1 < nch) { P4_WRITE(cbuf + ((ch + 1) & 1) * CBUF + tok * CTOK); if (ch + 2 < nch) P4_LOAD(ch + 2); }
;       f32x4 s0 = (f32x4){0.f, 0.f, 0.f, 0.f}, s1 = (f32x4){0.f, 0.f, 0.f, 0.f};
; #pragma unroll
;       for (int s = 0; s < 8; ++s) {
;         const bf16x8 a0 = *(const LAS bf16x8*)(cb + r16 * CROW + s * 64 + qoff);
;         const bf16x8 a1 = *(const LAS bf16x8*)(cb + (16 + r16) * CROW + s * 64 + qoff);
;         s0 = __builtin_amdgcn_mfma_f32_16x16x32_bf16(a0, qB[s], s0, 0, 0, 0);
;         s1 = __builtin_amdgcn_mfma_f32_16x16x32_bf16(a1, qB[s], s1, 0, 0, 0);
;       }
.Lp4_w1:
	s_bitcmp1_b32 s10, 0
	s_cbranch_scc1 .Lp4_w1_odd
	s_bitcmp1_b32 s10, 0
	s_cselect_b32 s11, 0x11000, 0
	s_add_i32 s12, s5, s11
	s_lshl_b32 s13, s10, 5
	v_add3_u32 v2, s12, v168, v162
	v_mov_b32_e32 v139, s2
	ds_read_b32 v138, v139
	ds_read_b128 v[234:237], v2
	ds_read_b128 v[238:241], v2 offset:8704
	ds_read_b128 v[242:245], v2 offset:64
	ds_read_b128 v[246:249], v2 offset:8768
	ds_read_b128 v[250:253], v2 offset:128
	ds_read_b128 v[188:191], v2 offset:8832
	v_or_b32_e32 v0, s13, v148
	v_lshl_add_u32 v3, v0, 1, s3
	s_bitcmp1_b32 s23, 0
	s_cselect_b32 s11, 0x11000, 0
	v_add_u32_e32 v201, s11, v170
	s_waitcnt lgkmcnt(5)
	v_mfma_f32_16x16x32_bf16 v[140:143], v[234:237], v[4:7], 0
	ds_read_b128 v[234:237], v2 offset:192
	s_waitcnt lgkmcnt(5)
	v_mfma_f32_16x16x32_bf16 v[144:147], v[238:241], v[4:7], 0
	ds_read_b128 v[238:241], v2 offset:8896
	ds_read2_b64 v[184:187], v3 offset1:4
	s_waitcnt lgkmcnt(6)
	v_mfma_f32_16x16x32_bf16 v[140:143], v[242:245], v[8:11], v[140:143]
	ds_read_b128 v[242:245], v2 offset:256
	v_cmp_le_u32_e32 vcc, s19, v138
	s_cbranch_vccz .Lp4_wbs_W10
.Lp4_wbk_W10:
	s_waitcnt vmcnt(7)
	ds_write_b128 v201, v[202:205]
	s_waitcnt lgkmcnt(7)
	v_mfma_f32_16x16x32_bf16 v[144:147], v[246:249], v[8:11], v[144:147]
	ds_read_b128 v[246:249], v2 offset:8960
	s_waitcnt vmcnt(6)
	ds_write_b128 v201, v[206:209] offset:544
	s_waitcnt lgkmcnt(8)
	v_mfma_f32_16x16x32_bf16 v[140:143], v[250:253], v[12:15], v[140:143]
	ds_read_b128 v[250:253], v2 offset:320
	s_waitcnt vmcnt(5)
	ds_write_b128 v201, v[210:213] offset:1088
	s_waitcnt lgkmcnt(9)
	v_mfma_f32_16x16x32_bf16 v[144:147], v[188:191], v[12:15], v[144:147]
	ds_read_b128 v[188:191], v2 offset:9024
	s_waitcnt vmcnt(4)
	ds_write_b128 v201, v[214:217] offset:1632
	s_waitcnt lgkmcnt(10)
	v_mfma_f32_16x16x32_bf16 v[140:143], v[234:237], v[16:19], v[140:143]
	ds_read_b128 v[234:237], v2 offset:384
	s_waitcnt vmcnt(3)
	ds_write_b128 v201, v[218:221] offset:2176
	s_waitcnt lgkmcnt(11)
	v_mfma_f32_16x16x32_bf16 v[144:147], v[238:241], v[16:19], v[144:147]
	ds_read_b128 v[238:241], v2 offset:9088
	s_waitcnt vmcnt(2)
	ds_write_b128 v201, v[222:225] offset:2720
	s_waitcnt lgkmcnt(11)
	v_mfma_f32_16x16x32_bf16 v[140:143], v[242:245], v[20:23], v[140:143]
	ds_read_b128 v[242:245], v2 offset:448
	s_waitcnt vmcnt(1)
	ds_write_b128 v201, v[226:229] offset:3264
	s_waitcnt lgkmcnt(11)
	v_mfma_f32_16x16x32_bf16 v[144:147], v[246:249], v[20:23], v[144:147]
	ds_read_b128 v[246:249], v2 offset:9152
	s_waitcnt vmcnt(0)
	ds_write_b128 v201, v[230:233] offset:3808
	s_waitcnt lgkmcnt(11)
	v_mfma_f32_16x16x32_bf16 v[140:143], v[250:253], v[24:27], v[140:143]
	s_waitcnt lgkmcnt(9)
	v_mfma_f32_16x16x32_bf16 v[144:147], v[188:191], v[24:27], v[144:147]
	s_waitcnt lgkmcnt(7)
	v_mfma_f32_16x16x32_bf16 v[140:143], v[234:237], v[28:31], v[140:143]
	s_waitcnt lgkmcnt(5)
	v_mfma_f32_16x16x32_bf16 v[144:147], v[238:241], v[28:31], v[144:147]
	s_waitcnt lgkmcnt(3)
	v_mfma_f32_16x16x32_bf16 v[140:143], v[242:245], v[32:35], v[140:143]
	s_waitcnt lgkmcnt(1)
	v_mfma_f32_16x16x32_bf16 v[144:147], v[246:249], v[32:35], v[144:147]
	s_branch .Lp4_softmax

; #define LAS __attribute__((address_space(3)))
; #define P4_LOAD(ch) do { const u32x4 kk_ = *(const LAS u32x4*)(idxs + tok * 256 + (ch) * 32 + wrow); \
;       _Pragma("unroll") for (int i = 0; i < 8; ++i) { \
;       const int key = (int)((kk_[i >> 1] >> (16 * (i & 1))) & 0xffffu); stg[i] = *(const u32x4*)(cbase + (size_t)key * 256); } } while (0)
; #define P4_WRITE(bufp) do { _Pragma("unroll") for (int i = 0; i < 8; ++i) \
;       *(LAS u32x4*)((bufp) + (wrow + i) * CROW + 16 * (wch ^ (lane >> 5))) = stg[i]; } while (0)
; __device__ __forceinline__ void pair_sync(LAS unsigned* cnt, unsigned target, int lane) {
;   asm volatile("" ::: "memory");
;   if (lane == 0) __hip_atomic_fetch_add(cnt, 1u, __ATOMIC_RELAXED, __HIP_MEMORY_SCOPE_WORKGROUP);
;   while (__hip_atomic_load(cnt, __ATOMIC_RELAXED, __HIP_MEMORY_SCOPE_WORKGROUP) < target) __builtin_amdgcn_s_sleep(1);
;   asm volatile("" ::: "memory");
; }
; __device__ __forceinline__ void p4_attn(const Params& p, unsigned char* lds, int bid, int nb, bool dry) {
;     ...
;     for (int ch = 0; ch < nch; ++ch) {
;       LAS unsigned char* cb = cbuf + (ch & 1) * CBUF + tok * CTOK;
;       if (ch + 1 < nch) { P4_WRITE(cbuf + ((ch + 1) & 1) * CBUF + tok * CTOK); if (ch + 2 < nch) P4_LOAD(ch + 2); }
;       f32x4 s0 = (f32x4){0.f, 0.f, 0.f, 0.f}, s1 = (f32x4){0.f, 0.f, 0.f, 0.f};
; #pragma unroll
;       for (int s = 0; s < 8; ++s) {
;         const bf16x8 a0 = *(const LAS bf16x8*)(cb + r16 * CROW + s * 64 + qoff);
;         const bf16x8 a1 = *(const LAS bf16x8*)(cb + (16 + r16) * CROW + s * 64 + qoff);
;         s0 = __builtin_amdgcn_mfma_f32_16x16x32_bf16(a0, qB[s], s0, 0, 0, 0);
;         s1 = __builtin_amdgcn_mfma_f32_16x16x32_bf16(a1, qB[s], s1, 0, 0, 0);
;       }
.Lp4_w1_odd:
	s_bitcmp1_b32 s10, 0
	s_cselect_b32 s11, 0x11000, 0
	s_add_i32 s12, s5, s11
	s_lshl_b32 s13, s10, 5
	v_add3_u32 v2, s12, v168, v162
	v_mov_b32_e32 v139, s2
	ds_read_b32 v138, v139
	ds_read_b128 v[234:237], v2
	ds_read_b128 v[238:241], v2 offset:8704
	ds_read_b128 v[242:245], v2 offset:64
	ds_read_b128 v[246:249], v2 offset:8768
	ds_read_b128 v[250:253], v2 offset:128
	ds_read_b128 v[188:191], v2 offset:8832
	v_or_b32_e32 v0, s13, v148
	v_lshl_add_u32 v3, v0, 1, s3
	s_bitcmp1_b32 s23, 0
	s_cselect_b32 s11, 0x11000, 0
	v_add_u32_e32 v201, s11, v170
	s_waitcnt lgkmcnt(5)
	v_mfma_f32_16x16x32_bf16 v[140:143], v[234:237], v[4:7], 0
	ds_read_b128 v[234:237], v2 offset:192
	s_waitcnt lgkmcnt(5)
	v_mfma_f32_16x16x32_bf16 v[144:147], v[238:241], v[4:7], 0
	ds_read_b128 v[238:241], v2 offset:8896
	ds_read2_b64 v[184:187], v3 offset1:4
	s_waitcnt lgkmcnt(6)
	v_mfma_f32_16x16x32_bf16 v[140:143], v[242:245], v[8:11], v[140:143]
	ds_read_b128 v[242:245], v2 offset:256
	v_cmp_le_u32_e32 vcc, s19, v138
	s_cbranch_vccz .Lp4_wbs_W11
.Lp4_wbk_W11:
	s_waitcnt vmcnt(7)
	ds_write_b128 v201, v[44:47]
	s_waitcnt lgkmcnt(7)
	v_mfma_f32_16x16x32_bf16 v[144:147], v[246:249], v[8:11], v[144:147]
	ds_read_b128 v[246:249], v2 offset:8960
	s_waitcnt vmcnt(6)
	ds_write_b128 v201, v[48:51] offset:544
	s_waitcnt lgkmcnt(8)
	v_mfma_f32_16x16x32_bf16 v[140:143], v[250:253], v[12:15], v[140:143]
	ds_read_b128 v[250:253], v2 offset:320
	s_waitcnt vmcnt(5)
	ds_write_b128 v201, v[60:63] offset:1088
	s_waitcnt lgkmcnt(9)
	v_mfma_f32_16x16x32_bf16 v[144:147], v[188:191], v[12:15], v[144:147]
	ds_read_b128 v[188:191], v2 offset:9024
	s_waitcnt vmcnt(4)
	ds_write_b128 v201, v[68:71] offset:1632
	s_waitcnt lgkmcnt(10)
	v_mfma_f32_16x16x32_bf16 v[140:143], v[234:237], v[16:19], v[140:143]
	ds_read_b128 v[234:237], v2 offset:384
	s_waitcnt vmcnt(3)
	ds_write_b128 v201, v[84:87] offset:2176
	s_waitcnt lgkmcnt(11)
	v_mfma_f32_16x16x32_bf16 v[144:147], v[238:241], v[16:19], v[144:147]
	ds_read_b128 v[238:241], v2 offset:9088
	s_waitcnt vmcnt(2)
	ds_write_b128 v201, v[88:91] offset:2720
	s_waitcnt lgkmcnt(11)
	v_mfma_f32_16x16x32_bf16 v[140:143], v[242:245], v[20:23], v[140:143]
	ds_read_b128 v[242:245], v2 offset:448
	s_waitcnt vmcnt(1)
	ds_write_b128 v201, v[100:103] offset:3264
	s_waitcnt lgkmcnt(11)
	v_mfma_f32_16x16x32_bf16 v[144:147], v[246:249], v[20:23], v[144:147]
	ds_read_b128 v[246:249], v2 offset:9152
	s_waitcnt vmcnt(0)
	ds_write_b128 v201, v[108:111] offset:3808
	s_waitcnt lgkmcnt(11)
	v_mfma_f32_16x16x32_bf16 v[140:143], v[250:253], v[24:27], v[140:143]
	s_waitcnt lgkmcnt(9)
	v_mfma_f32_16x16x32_bf16 v[144:147], v[188:191], v[24:27], v[144:147]
	s_waitcnt lgkmcnt(7)
	v_mfma_f32_16x16x32_bf16 v[140:143], v[234:237], v[28:31], v[140:143]
	s_waitcnt lgkmcnt(5)
	v_mfma_f32_16x16x32_bf16 v[144:147], v[238:241], v[28:31], v[144:147]
	s_waitcnt lgkmcnt(3)
	v_mfma_f32_16x16x32_bf16 v[140:143], v[242:245], v[32:35], v[140:143]
	s_waitcnt lgkmcnt(1)
	v_mfma_f32_16x16x32_bf16 v[144:147], v[246:249], v[32:35], v[144:147]
	s_branch .Lp4_softmax

; #define LAS __attribute__((address_space(3)))
; __device__ __forceinline__ void pair_sync(LAS unsigned* cnt, unsigned target, int lane) {
;   asm volatile("" ::: "memory");
;   if (lane == 0) __hip_atomic_fetch_add(cnt, 1u, __ATOMIC_RELAXED, __HIP_MEMORY_SCOPE_WORKGROUP);
;   while (__hip_atomic_load(cnt, __ATOMIC_RELAXED, __HIP_MEMORY_SCOPE_WORKGROUP) < target) __builtin_amdgcn_s_sleep(1);
;   asm volatile("" ::: "memory");
; }
; __device__ __forceinline__ void p4_attn(const Params& p, unsigned char* lds, int bid, int nb, bool dry) {
;     ...
;       const int slotb = ch * 32 + 4 * g;
;       const u32x2 k0 = *(const LAS u32x2*)(idxs + tok * 256 + slotb), k1 = *(const LAS u32x2*)(idxs + tok * 256 + slotb + 16);
;       float lg0[4], lg1[4]; float mx = -1e30f;
;       const bool full = (ch * 32 + 32 <= nk);
;       int dd0[4], dd1[4]; int dmin = 1 << 20;
; #pragma unroll
;       for (int i = 0; i < 4; ++i) {
;         const int key0 = (int)((k0[i >> 1] >> (16 * (i & 1))) & 0xffffu), key1 = (int)((k1[i >> 1] >> (16 * (i & 1))) & 0xffffu);
;         dd0[i] = t - key0; dd1[i] = t - key1; dmin = min(dmin, min(dd0[i], dd1[i]));
;       }
;       if (__ballot(dmin < 128) == 0ull) {
;         const float bfar = biasd[128 * 32 + head];
; #pragma unroll
;         for (int i = 0; i < 4; ++i) { lg0[i] = s0[i] * SC + bfar; lg1[i] = s1[i] * SC + bfar; }
;       } else {
; #pragma unroll
;         for (int i = 0; i < 4; ++i) {
;           const int d0 = min(max(dd0[i], 0), 128), d1 = min(max(dd1[i], 0), 128);
;           lg0[i] = s0[i] * SC + biasd[d0 * 32 + head];
;           lg1[i] = s1[i] * SC + biasd[d1 * 32 + head];
;         }
;       }
.Lp4_softmax:
	s_waitcnt lgkmcnt(0)
	s_mov_b64 s[24:25], exec
	s_mov_b64 exec, s[8:9]
	v_mov_b32_e32 v193, s2
	v_mov_b32_e32 v138, 1
	ds_add_u32 v193, v138
	s_mov_b64 exec, s[24:25]
	s_add_i32 s19, s19, 2
	v_or_b32_e32 v0, s13, v148
	v_add_u32_e32 v192, s12, v163
	v_add3_u32 v192, v192, v164, v165
	v_sub_u32_sdwa v3, s14, v187 dst_sel:DWORD dst_unused:UNUSED_PAD src0_sel:DWORD src1_sel:WORD_1
	v_sub_u32_sdwa v136, s14, v184 dst_sel:DWORD dst_unused:UNUSED_PAD src0_sel:DWORD src1_sel:WORD_0
	v_sub_u32_sdwa v137, s14, v186 dst_sel:DWORD dst_unused:UNUSED_PAD src0_sel:DWORD src1_sel:WORD_0
	v_sub_u32_sdwa v134, s14, v184 dst_sel:DWORD dst_unused:UNUSED_PAD src0_sel:DWORD src1_sel:WORD_1
	v_sub_u32_sdwa v135, s14, v186 dst_sel:DWORD dst_unused:UNUSED_PAD src0_sel:DWORD src1_sel:WORD_1
	v_sub_u32_sdwa v132, s14, v185 dst_sel:DWORD dst_unused:UNUSED_PAD src0_sel:DWORD src1_sel:WORD_0
	v_sub_u32_sdwa v133, s14, v187 dst_sel:DWORD dst_unused:UNUSED_PAD src0_sel:DWORD src1_sel:WORD_0
	v_sub_u32_sdwa v2, s14, v185 dst_sel:DWORD dst_unused:UNUSED_PAD src0_sel:DWORD src1_sel:WORD_1
	v_min_i32_e32 v138, v134, v135
	v_min3_i32 v138, v136, v137, v138
	v_min_i32_e32 v139, v132, v133
	v_min_i32_e32 v193, v2, v3
	v_min3_i32 v138, v138, v139, v193
	v_cmp_gt_i32_e32 vcc, s16, v138
	s_cbranch_vccz .Lp4_far
	v_med3_i32 v136, v136, 0, v172
	v_med3_i32 v137, v137, 0, v172
	v_med3_i32 v132, v132, 0, v172
	v_med3_i32 v133, v133, 0, v172
	v_med3_i32 v2, v2, 0, v172
	v_med3_i32 v134, v134, 0, v172
	v_med3_i32 v135, v135, 0, v172
	v_med3_i32 v3, v3, 0, v172
	v_lshl_add_u32 v136, v136, 7, v169
	v_lshl_add_u32 v137, v137, 7, v169
	v_lshl_add_u32 v132, v132, 7, v169
	v_lshl_add_u32 v133, v133, 7, v169
	v_lshl_add_u32 v139, v2, 7, v169
	v_lshl_add_u32 v134, v134, 7, v169
	v_lshl_add_u32 v135, v135, 7, v169
	v_lshl_add_u32 v193, v3, 7, v169
	ds_read_b32 v2, v136
	ds_read_b32 v136, v137
	ds_read_b32 v132, v132
	ds_read_b32 v138, v133
	ds_read_b32 v133, v139
	ds_read_b32 v3, v134
	ds_read_b32 v139, v193
	ds_read_b32 v137, v135
	ds_read_b64_tr_b16 v[234:235], v192
	ds_read_b64_tr_b16 v[236:237], v192 offset:8704
	ds_read_b64_tr_b16 v[238:239], v192 offset:32
	ds_read_b64_tr_b16 v[240:241], v192 offset:8736
	ds_read_b64_tr_b16 v[242:243], v192 offset:64
	ds_read_b64_tr_b16 v[244:245], v192 offset:8768
	s_waitcnt lgkmcnt(6)
	v_pk_fma_f32 v[134:135], v[142:143], s[4:5], v[132:133] op_sel_hi:[1,0,1]
	v_pk_fma_f32 v[132:133], v[140:141], s[4:5], v[2:3] op_sel_hi:[1,0,1]
	v_pk_fma_f32 v[138:139], v[146:147], s[4:5], v[138:139] op_sel_hi:[1,0,1]
	v_pk_fma_f32 v[136:137], v[144:145], s[4:5], v[136:137] op_sel_hi:[1,0,1]
	ds_read_b64_tr_b16 v[246:247], v192 offset:96
	ds_read_b64_tr_b16 v[248:249], v192 offset:8800
	ds_read_b64_tr_b16 v[250:251], v192 offset:128
	ds_read_b64_tr_b16 v[252:253], v192 offset:8832
	ds_read_b64_tr_b16 v[188:189], v192 offset:160
	ds_read_b64_tr_b16 v[190:191], v192 offset:8864
	ds_read_b64_tr_b16 v[176:177], v192 offset:192
	ds_read_b64_tr_b16 v[178:179], v192 offset:8896
	s_branch .Lp4_lg

; #define LAS __attribute__((address_space(3)))
; __device__ __forceinline__ u32x4 pack8(f32x4 a, f32x4 b) { u32x4 w; w[0] = cvt_pk_bf16(a[0], a[1]); w[1] = cvt_pk_bf16(a[2], a[3]); w[2] = cvt_pk_bf16(b[0], b[1]); w[3] = cvt_pk_bf16(b[2], b[3]); return w; }
; __device__ __forceinline__ void pair_sync(LAS unsigned* cnt, unsigned target, int lane) {
;   asm volatile("" ::: "memory");
;   if (lane == 0) __hip_atomic_fetch_add(cnt, 1u, __ATOMIC_RELAXED, __HIP_MEMORY_SCOPE_WORKGROUP);
;   while (__hip_atomic_load(cnt, __ATOMIC_RELAXED, __HIP_MEMORY_SCOPE_WORKGROUP) < target) __builtin_amdgcn_s_sleep(1);
;   asm volatile("" ::: "memory");
; }
; __device__ __forceinline__ void p4_attn(const Params& p, unsigned char* lds, int bid, int nb, bool dry) {
;     ...
;       float ps = 0.f; f32x4 p0, p1;
; #pragma unroll
;       for (int i = 0; i < 4; ++i) { p0[i] = __builtin_amdgcn_exp2f(lg0[i] - m_run); p1[i] = __builtin_amdgcn_exp2f(lg1[i] - m_run); ps += p0[i] + p1[i]; }
;       l_run = l_run * alpha + ps;
;       const u32x4 pw = pack8(p0, p1);
;       bf16x8 pb; { union { u32x4 u; bf16x8 v; } cv; cv.u = pw; pb = cv.v; }
;       LAS unsigned char* trb = cb + troff;
; #pragma unroll
;       for (int ct = 0; ct < 16; ++ct) {
;         const s16x4 ta = __builtin_amdgcn_ds_read_tr16_b64_v4i16((LAS s16x4*)(trb + 32 * ct));
;         const s16x4 tb = __builtin_amdgcn_ds_read_tr16_b64_v4i16((LAS s16x4*)(trb + 16 * CROW + 32 * ct));
;         const bf16x8 a = {ta[0], ta[1], ta[2], ta[3], tb[0], tb[1], tb[2], tb[3]};
;         o[ct] = __builtin_amdgcn_mfma_f32_16x16x32_bf16(a, pb, o[ct], 0, 0, 0);
;       }
;       epoch += 2u; pair_sync(pcnt, epoch, lane);
.Lp4_exp:
	v_sub_f32_e32 v2, v132, v175
	v_sub_f32_e32 v3, v136, v175
	v_sub_f32_e32 v132, v133, v175
	v_sub_f32_e32 v133, v137, v175
	v_sub_f32_e32 v136, v138, v175
	v_sub_f32_e32 v137, v139, v175
	v_sub_f32_e32 v134, v134, v175
	v_sub_f32_e32 v135, v135, v175
	v_exp_f32_e32 v2, v2
	v_exp_f32_e32 v3, v3
	v_exp_f32_e32 v132, v132
	v_exp_f32_e32 v133, v133
	v_exp_f32_e32 v134, v134
	v_exp_f32_e32 v136, v136
	v_exp_f32_e32 v135, v135
	v_exp_f32_e32 v137, v137
	v_cvt_pk_bf16_f32 v138, v2, v132
	v_cvt_pk_bf16_f32 v139, v134, v135
	v_cvt_pk_bf16_f32 v140, v3, v133
	v_cvt_pk_bf16_f32 v141, v136, v137
	s_nop 1
	v_mov_b32_e32 v144, s2
	s_waitcnt lgkmcnt(12)
	v_mfma_f32_16x16x32_bf16 v[128:131], v[234:237], v[138:141], v[128:131]
	ds_read_b64_tr_b16 v[180:181], v192 offset:224
	ds_read_b64_tr_b16 v[182:183], v192 offset:8928
	s_waitcnt lgkmcnt(12)
	v_mfma_f32_16x16x32_bf16 v[124:127], v[238:241], v[138:141], v[124:127]
	ds_read_b64_tr_b16 v[234:235], v192 offset:256
	ds_read_b64_tr_b16 v[236:237], v192 offset:8960
	s_waitcnt lgkmcnt(12)
	v_mfma_f32_16x16x32_bf16 v[120:123], v[242:245], v[138:141], v[120:123]
	ds_read_b64_tr_b16 v[238:239], v192 offset:288
	ds_read_b64_tr_b16 v[240:241], v192 offset:8992
	s_waitcnt lgkmcnt(12)
	v_mfma_f32_16x16x32_bf16 v[116:119], v[246:249], v[138:141], v[116:119]
	ds_read_b64_tr_b16 v[242:243], v192 offset:320
	ds_read_b64_tr_b16 v[244:245], v192 offset:9024
	s_waitcnt lgkmcnt(12)
	v_mfma_f32_16x16x32_bf16 v[112:115], v[250:253], v[138:141], v[112:115]
	ds_read_b64_tr_b16 v[246:247], v192 offset:352
	ds_read_b64_tr_b16 v[248:249], v192 offset:9056
	s_waitcnt lgkmcnt(12)
	v_mfma_f32_16x16x32_bf16 v[104:107], v[188:191], v[138:141], v[104:107]
	ds_read_b64_tr_b16 v[250:251], v192 offset:384
	ds_read_b64_tr_b16 v[252:253], v192 offset:9088
	s_waitcnt lgkmcnt(12)
	v_mfma_f32_16x16x32_bf16 v[96:99], v[176:179], v[138:141], v[96:99]
	ds_read_b64_tr_b16 v[188:189], v192 offset:416
	ds_read_b64_tr_b16 v[190:191], v192 offset:9120
	s_waitcnt lgkmcnt(12)
	v_mfma_f32_16x16x32_bf16 v[92:95], v[180:183], v[138:141], v[92:95]
	ds_read_b64_tr_b16 v[176:177], v192 offset:448
	ds_read_b64_tr_b16 v[178:179], v192 offset:9152
	s_waitcnt lgkmcnt(12)
	v_mfma_f32_16x16x32_bf16 v[80:83], v[234:237], v[138:141], v[80:83]
	ds_read_b64_tr_b16 v[180:181], v192 offset:480
	ds_read_b64_tr_b16 v[182:183], v192 offset:9184
	ds_read_b32 v145, v144
	s_waitcnt lgkmcnt(13)
	v_mfma_f32_16x16x32_bf16 v[76:79], v[238:241], v[138:141], v[76:79]
	s_waitcnt lgkmcnt(11)
	v_mfma_f32_16x16x32_bf16 v[72:75], v[242:245], v[138:141], v[72:75]
	s_waitcnt lgkmcnt(9)
	v_mfma_f32_16x16x32_bf16 v[64:67], v[246:249], v[138:141], v[64:67]
	s_waitcnt lgkmcnt(7)
	v_mfma_f32_16x16x32_bf16 v[56:59], v[250:253], v[138:141], v[56:59]
	s_waitcnt lgkmcnt(5)
	v_mfma_f32_16x16x32_bf16 v[52:55], v[188:191], v[138:141], v[52:55]
	s_waitcnt lgkmcnt(3)
	v_mfma_f32_16x16x32_bf16 v[40:43], v[176:179], v[138:141], v[40:43]
	s_waitcnt lgkmcnt(1)
	v_mfma_f32_16x16x32_bf16 v[36:39], v[180:183], v[138:141], v[36:39]
	s_waitcnt lgkmcnt(0)
	v_cmp_le_u32_e32 vcc, s19, v145
	s_cbranch_vccnz .Lp4_wa_ok
.Lp4_wa_spin:
	s_sleep 1
	ds_read_b32 v145, v144
	s_waitcnt lgkmcnt(0)
	v_cmp_gt_u32_e32 vcc, s19, v145
	s_cbranch_vccnz .Lp4_wa_spin
.Lp4_wa_ok:
	s_mov_b64 s[24:25], exec
	s_mov_b64 exec, s[8:9]
	v_mov_b32_e32 v145, 1
	ds_add_u32 v144, v145
	s_mov_b64 exec, s[24:25]
	s_add_i32 s19, s19, 2
	s_cmp_eq_u32 s23, s22
	s_cbranch_scc0 .Lp4_nofull
.Lp4_full:
	ds_read_b32 v145, v144
	s_waitcnt lgkmcnt(0)
	v_cmp_gt_u32_e32 vcc, s19, v145
	s_cbranch_vccz .Lp4_nofull
	s_sleep 1
	s_branch .Lp4_full
; #define LAS __attribute__((address_space(3)))
; __device__ __forceinline__ u32x4 pack8(f32x4 a, f32x4 b) { u32x4 w; w[0] = cvt_pk_bf16(a[0], a[1]); w[1] = cvt_pk_bf16(a[2], a[3]); w[2] = cvt_pk_bf16(b[0], b[1]); w[3] = cvt_pk_bf16(b[2], b[3]); return w; }
; __device__ __forceinline__ float psum16(float x) { const u32x2s r = __builtin_amdgcn_permlane16_swap(__float_as_uint(x), __float_as_uint(x), false, false); return __uint_as_float(r[0]) + __uint_as_float(r[1]); }
; __device__ __forceinline__ void p4_attn(const Params& p, unsigned char* lds, int bid, int nb, bool dry) {
;     ...
;       for (int i = 0; i < 4; ++i) { p0[i] = __builtin_amdgcn_exp2f(lg0[i] - m_run); p1[i] = __builtin_amdgcn_exp2f(lg1[i] - m_run); ps += p0[i] + p1[i]; }
;       l_run = l_run * alpha + ps;
;       const u32x4 pw = pack8(p0, p1);
;       bf16x8 pb; { union { u32x4 u; bf16x8 v; } cv; cv.u = pw; pb = cv.v; }
;       LAS unsigned char* trb = cb + troff;
; #pragma unroll
;       for (int ct = 0; ct < 16; ++ct) {
;         const s16x4 ta = __builtin_amdgcn_ds_read_tr16_b64_v4i16((LAS s16x4*)(trb + 32 * ct));
;         const s16x4 tb = __builtin_amdgcn_ds_read_tr16_b64_v4i16((LAS s16x4*)(trb + 16 * CROW + 32 * ct));
;         const bf16x8 a = {ta[0], ta[1], ta[2], ta[3], tb[0], tb[1], tb[2], tb[3]};
;         o[ct] = __builtin_amdgcn_mfma_f32_16x16x32_bf16(a, pb, o[ct], 0, 0, 0);
;       }
;       epoch += 2u; pair_sync(pcnt, epoch, lane);
;     }
;     const float l = psum32(psum16(l_run));
;     const float inv = 16.f / l;
;     unsigned char* orow = qrow + 4 * g;
; #pragma unroll
;     for (int ct = 0; ct < 16; ++ct) {
;       unsigned w = __builtin_amdgcn_cvt_pk_fp8_f32(o[ct][0] * inv, o[ct][1] * inv, 0, false); w = __builtin_amdgcn_cvt_pk_fp8_f32(o[ct][2] * inv, o[ct][3] * inv, w, true);
;       if (!dry) *(unsigned*)(orow + 16 * ct) = w;
;     }
; __device__ __forceinline__ void grid_bar(unsigned* ctr, unsigned target) {
;   __syncthreads();
;   if (threadIdx.x == 0) {
;     __builtin_amdgcn_fence(__ATOMIC_RELEASE, "agent");
;     asm volatile("s_waitcnt vmcnt(0)" ::: "memory");
;     __hip_atomic_fetch_add(ctr, 1u, __ATOMIC_RELAXED, __HIP_MEMORY_SCOPE_AGENT);
;     while (__hip_atomic_load(ctr, __ATOMIC_RELAXED, __HIP_MEMORY_SCOPE_AGENT) < target) __builtin_amdgcn_s_sleep(2);
.Lp4_nofull:
.LBB0_1019:
	v_add_f32_e32 v2, v2, v3
	v_add_f32_e32 v3, v132, v133
	v_add_f32_e32 v2, 0, v2
	v_add_f32_e32 v132, v134, v136
	v_add_f32_e32 v2, v3, v2
	v_add_f32_e32 v133, v135, v137
	v_add_f32_e32 v2, v132, v2
	v_add_f32_e32 v2, v133, v2
	v_fmac_f32_e32 v2, v174, v0
	s_cmp_eq_u32 s23, s22
	s_cbranch_scc0 .LBB0_1004
	v_mov_b32_e32 v0, v2
	s_nop 1
	v_permlane16_swap_b32_e32 v2, v0
	v_add_f32_e32 v0, v2, v0
	v_mov_b32_e32 v2, v0
	s_nop 1
	v_permlane32_swap_b32_e32 v0, v2
	v_add_f32_e32 v0, v0, v2
	v_div_scale_f32 v2, s[10:11], v0, v0, s18
	v_rcp_f32_e32 v3, v2
	v_mov_b32_e32 v7, v1
	s_add_i32 s20, s20, 1
	s_mul_i32 s10, s20, s89
	v_fma_f32 v4, -v2, v3, 1.0
	v_fmac_f32_e32 v3, v4, v3
	v_div_scale_f32 v4, vcc, s18, v0, s18
	v_mul_f32_e32 v5, v4, v3
	v_fma_f32 v6, -v2, v5, v4
	v_fmac_f32_e32 v5, v6, v3
	v_fma_f32 v2, -v2, v5, v4
	v_div_fmas_f32 v2, v2, v3, v5
	v_div_fixup_f32 v0, v2, v0, s18
	v_mul_f32_e32 v20, v128, v0
	v_mul_f32_e32 v21, v129, v0
	v_mov_b32_e32 v4, v1
	v_cvt_pk_fp8_f32 v4, v20, v21
	v_mul_f32_e32 v22, v130, v0
	v_mul_f32_e32 v23, v131, v0
	v_cvt_pk_fp8_f32 v4, v22, v23 op_sel:[0,0,1]
	v_mul_f32_e32 v20, v124, v0
	v_mul_f32_e32 v21, v125, v0
	v_mov_b32_e32 v5, v1
	v_cvt_pk_fp8_f32 v5, v20, v21
	v_mul_f32_e32 v22, v126, v0
	v_mul_f32_e32 v23, v127, v0
	v_cvt_pk_fp8_f32 v5, v22, v23 op_sel:[0,0,1]
	v_mul_f32_e32 v20, v120, v0
	v_mul_f32_e32 v21, v121, v0
	v_mov_b32_e32 v6, v1
	v_cvt_pk_fp8_f32 v6, v20, v21
	v_mul_f32_e32 v22, v122, v0
	v_mul_f32_e32 v23, v123, v0
	v_cvt_pk_fp8_f32 v6, v22, v23 op_sel:[0,0,1]
	v_mul_f32_e32 v20, v116, v0
	v_mul_f32_e32 v21, v117, v0
	v_mov_b32_e32 v7, v1
	v_cvt_pk_fp8_f32 v7, v20, v21
	v_mul_f32_e32 v22, v118, v0
	v_mul_f32_e32 v23, v119, v0
	v_cvt_pk_fp8_f32 v7, v22, v23 op_sel:[0,0,1]
	v_mul_f32_e32 v20, v112, v0
	v_mul_f32_e32 v21, v113, v0
	v_mov_b32_e32 v8, v1
	v_cvt_pk_fp8_f32 v8, v20, v21
	v_mul_f32_e32 v22, v114, v0
	v_mul_f32_e32 v23, v115, v0
	v_cvt_pk_fp8_f32 v8, v22, v23 op_sel:[0,0,1]
	v_mul_f32_e32 v20, v104, v0
	v_mul_f32_e32 v21, v105, v0
	v_mov_b32_e32 v9, v1
	v_cvt_pk_fp8_f32 v9, v20, v21
	v_mul_f32_e32 v22, v106, v0
	v_mul_f32_e32 v23, v107, v0
	v_cvt_pk_fp8_f32 v9, v22, v23 op_sel:[0,0,1]
	v_mul_f32_e32 v20, v96, v0
	v_mul_f32_e32 v21, v97, v0
	v_mov_b32_e32 v10, v1
	v_cvt_pk_fp8_f32 v10, v20, v21
	v_mul_f32_e32 v22, v98, v0
	v_mul_f32_e32 v23, v99, v0
	v_cvt_pk_fp8_f32 v10, v22, v23 op_sel:[0,0,1]
	v_mul_f32_e32 v20, v92, v0
	v_mul_f32_e32 v21, v93, v0
	v_mov_b32_e32 v11, v1
	v_cvt_pk_fp8_f32 v11, v20, v21
	v_mul_f32_e32 v22, v94, v0
	v_mul_f32_e32 v23, v95, v0
	v_cvt_pk_fp8_f32 v11, v22, v23 op_sel:[0,0,1]
	v_mul_f32_e32 v20, v80, v0
	v_mul_f32_e32 v21, v81, v0
	v_mov_b32_e32 v12, v1
	v_cvt_pk_fp8_f32 v12, v20, v21
	v_mul_f32_e32 v22, v82, v0
	v_mul_f32_e32 v23, v83, v0
	v_cvt_pk_fp8_f32 v12, v22, v23 op_sel:[0,0,1]
	v_mul_f32_e32 v20, v76, v0
	v_mul_f32_e32 v21, v77, v0
	v_mov_b32_e32 v13, v1
	v_cvt_pk_fp8_f32 v13, v20, v21
	v_mul_f32_e32 v22, v78, v0
	v_mul_f32_e32 v23, v79, v0
	v_cvt_pk_fp8_f32 v13, v22, v23 op_sel:[0,0,1]
	v_mul_f32_e32 v20, v72, v0
	v_mul_f32_e32 v21, v73, v0
	v_mov_b32_e32 v14, v1
	v_cvt_pk_fp8_f32 v14, v20, v21
	v_mul_f32_e32 v22, v74, v0
	v_mul_f32_e32 v23, v75, v0
	v_cvt_pk_fp8_f32 v14, v22, v23 op_sel:[0,0,1]
	v_mul_f32_e32 v20, v64, v0
	v_mul_f32_e32 v21, v65, v0
	v_mov_b32_e32 v15, v1
	v_cvt_pk_fp8_f32 v15, v20, v21
	v_mul_f32_e32 v22, v66, v0
	v_mul_f32_e32 v23, v67, v0
	v_cvt_pk_fp8_f32 v15, v22, v23 op_sel:[0,0,1]
	v_mul_f32_e32 v20, v56, v0
	v_mul_f32_e32 v21, v57, v0
	v_mov_b32_e32 v16, v1
	v_cvt_pk_fp8_f32 v16, v20, v21
	v_mul_f32_e32 v22, v58, v0
	v_mul_f32_e32 v23, v59, v0
	v_cvt_pk_fp8_f32 v16, v22, v23 op_sel:[0,0,1]
	v_mul_f32_e32 v20, v52, v0
	v_mul_f32_e32 v21, v53, v0
	v_mov_b32_e32 v17, v1
	v_cvt_pk_fp8_f32 v17, v20, v21
	v_mul_f32_e32 v22, v54, v0
	v_mul_f32_e32 v23, v55, v0
	v_cvt_pk_fp8_f32 v17, v22, v23 op_sel:[0,0,1]
	v_mul_f32_e32 v20, v40, v0
	v_mul_f32_e32 v21, v41, v0
	v_mov_b32_e32 v18, v1
	v_cvt_pk_fp8_f32 v18, v20, v21
	v_mul_f32_e32 v22, v42, v0
	v_mul_f32_e32 v23, v43, v0
	v_cvt_pk_fp8_f32 v18, v22, v23 op_sel:[0,0,1]
	v_mul_f32_e32 v20, v36, v0
	v_mul_f32_e32 v21, v37, v0
	v_mov_b32_e32 v19, v1
	v_cvt_pk_fp8_f32 v19, v20, v21
	v_mul_f32_e32 v22, v38, v0
	v_mul_f32_e32 v23, v39, v0
	v_cvt_pk_fp8_f32 v19, v22, v23 op_sel:[0,0,1]
	v_lshlrev_b32_e32 v24, 2, v148
	v_mov_b32_e32 v25, 0
	v_lshl_add_u64 v[24:25], v[158:159], 0, v[24:25]
	s_add_i32 s1, s1, s89
	s_cmpk_gt_i32 s10, 0x1fff
	s_nop 1
	v_permlane32_swap_b32_e32 v4, v6
	v_permlane32_swap_b32_e32 v5, v7
	v_permlane32_swap_b32_e32 v8, v10
	v_permlane32_swap_b32_e32 v9, v11
	v_permlane32_swap_b32_e32 v12, v14
	v_permlane32_swap_b32_e32 v13, v15
	v_permlane32_swap_b32_e32 v16, v18
	v_permlane32_swap_b32_e32 v17, v19
	v_permlane16_swap_b32_e32 v4, v5
	v_permlane16_swap_b32_e32 v6, v7
	v_permlane16_swap_b32_e32 v8, v9
	v_permlane16_swap_b32_e32 v10, v11
	v_permlane16_swap_b32_e32 v12, v13
	v_permlane16_swap_b32_e32 v14, v15
	v_permlane16_swap_b32_e32 v16, v17
	v_permlane16_swap_b32_e32 v18, v19
	s_nop 1
	global_store_dwordx4 v[24:25], v[4:7], off
	global_store_dwordx4 v[24:25], v[8:11], off offset:64
	global_store_dwordx4 v[24:25], v[12:15], off offset:128
	global_store_dwordx4 v[24:25], v[16:19], off offset:192
	s_cbranch_scc0 .LBB0_991
	s_barrier
	s_barrier
	s_mov_b64 s[4:5], exec
	v_readlane_b32 s0, v254, 44
	v_readlane_b32 s1, v254, 45
	s_and_b64 s[0:1], s[4:5], s[0:1]
	s_mov_b64 exec, s[0:1]
	s_cbranch_execz .LBB0_1028
	s_mov_b64 s[8:9], exec
	buffer_wbl2 sc1
	s_waitcnt vmcnt(0)
	s_waitcnt vmcnt(0)
	v_mbcnt_lo_u32_b32 v0, s8, 0
	v_mbcnt_hi_u32_b32 v0, s9, v0
	v_cmp_eq_u32_e32 vcc, 0, v0
	s_and_saveexec_b64 s[10:11], vcc
	s_cbranch_execz .LBB0_1024
	s_bcnt1_i32_b64 s0, s[8:9]
	v_mov_b32_e32 v1, s0
	v_readlane_b32 s0, v254, 20
	v_mov_b32_e32 v0, 0
	v_readlane_b32 s1, v254, 21
	s_nop 4
	global_atomic_add v0, v1, s[0:1]
